# phase_out epilogue loads batched (hand-written); dnprep conv-weight loads hoisted to the which-loop top
# speedup vs baseline: 1.1606x; 1.0115x over previous
; #define RAWLOAD(w_) RAWLOAD_AT(w_,tok0,rs,re,h)
; __device__ __forceinline__ void phase_dnprep(KP kp_){ asm volatile("" : "+s"(kp_)); const Params p=load_params(kp_);
;     ...
;     if (!have_raw) RAWLOAD(0);
;     _Pragma("unroll 1") for (int which=0; which<3; ++which){
;       asm volatile("" : "+v"(tid));
;       RAWPUT1(rp0,tid); RAWPUT1(rp1,tid+512); RAWPUT1(rp2,tid+1024);
;       if (which<2) RAWLOAD(which+1);
;       __syncthreads();
;       int c=tid&127, tg=tid>>7; int ch=which*1024+h*128+c;
;       float w0=p.dn_conv_w[ch], w1=p.dn_conv_w[3072+ch], w2=p.dn_conv_w[6144+ch], w3=p.dn_conv_w[9216+ch], w4=p.dn_conv_w[12288+ch];
.LBB0_666:
	s_nop 0
	s_waitcnt vmcnt(0)
	s_or_b32 s12, s18, s74
	v_and_b32_e32 v229, 0x7f, v46
	v_or_b32_e32 v229, s12, v229
	v_lshlrev_b32_e32 v229, 2, v229
	v_add_u32_e32 v230, 0x3000, v229
	v_add_u32_e32 v231, 0x6000, v229
	v_add_u32_e32 v232, 0x9000, v229
	v_add_u32_e32 v233, 0xc000, v229
	global_load_dword v224, v229, s[20:21]
	global_load_dword v225, v230, s[20:21]
	global_load_dword v226, v231, s[20:21]
	global_load_dword v227, v232, s[20:21]
	global_load_dword v228, v233, s[20:21]
	v_lshlrev_b32_e32 v2, 5, v46
	v_cmp_gt_i32_e32 vcc, s64, v46
	v_and_b32_e32 v0, 0x1e0, v2
	s_and_saveexec_b64 s[10:11], vcc
	s_cbranch_execz .LBB0_668
	v_and_b32_e32 v2, 0xfffffe00, v2
	v_add3_u32 v2, 0, v2, v0
	v_lshlrev_b32_e32 v16, 16, v4
	v_and_b32_e32 v17, 0xffff0000, v4
	v_lshlrev_b32_e32 v18, 16, v5
	v_and_b32_e32 v19, 0xffff0000, v5
	ds_write_b128 v2, v[16:19]
	v_lshlrev_b32_e32 v16, 16, v6
	v_and_b32_e32 v17, 0xffff0000, v6
	v_lshlrev_b32_e32 v18, 16, v7
	v_and_b32_e32 v19, 0xffff0000, v7
	ds_write_b128 v2, v[16:19] offset:16

; __device__ __forceinline__ void phase_dnprep(KP kp_){ asm volatile("" : "+s"(kp_)); const Params p=load_params(kp_);
;     ...
;       int c=tid&127, tg=tid>>7; int ch=which*1024+h*128+c;
;       float w0=p.dn_conv_w[ch], w1=p.dn_conv_w[3072+ch], w2=p.dn_conv_w[6144+ch], w3=p.dn_conv_w[9216+ch], w4=p.dn_conv_w[12288+ch];
;       float o16[16];
;       { float rw[20];
;         _Pragma("unroll") for (int i=0;i<20;++i) rw[i]=raw[(tg*16+i)*128+c];
.LBB0_680:
	v_and_b32_e32 v50, 0x7f, v46
	s_or_b32 s12, s18, s12
	v_or_b32_e32 v0, s12, v50
	v_lshl_add_u64 v[2:3], v[0:1], 2, s[20:21]
	v_add_co_u32_e32 v16, vcc, 0x3000, v2
	s_waitcnt lgkmcnt(0)
	s_nop 0
	v_addc_co_u32_e32 v17, vcc, 0, v3, vcc
	v_add_co_u32_e32 v18, vcc, s63, v2
	s_barrier
	s_nop 0
	v_addc_co_u32_e32 v19, vcc, 0, v3, vcc
	v_add_co_u32_e32 v20, vcc, 0x9000, v2
	s_nop 1
	v_addc_co_u32_e32 v21, vcc, 0, v3, vcc
	v_add_co_u32_e32 v2, vcc, s44, v2
	v_ashrrev_i32_e32 v51, 7, v46
	s_nop 0
	v_addc_co_u32_e32 v3, vcc, 0, v3, vcc
	v_lshlrev_b32_e32 v2, 13, v51
	v_lshlrev_b32_e32 v3, 2, v50
	v_add3_u32 v29, 0, v2, v3
	ds_read2st64_b32 v[2:3], v29 offset1:2
	ds_read2st64_b32 v[16:17], v29 offset0:4 offset1:6
	ds_read2st64_b32 v[18:19], v29 offset0:8 offset1:10
	ds_read2st64_b32 v[20:21], v29 offset0:12 offset1:14
	ds_read2st64_b32 v[22:23], v29 offset0:16 offset1:18
	ds_read2st64_b32 v[32:33], v29 offset0:20 offset1:22
	ds_read2st64_b32 v[36:37], v29 offset0:24 offset1:26
	ds_read2st64_b32 v[34:35], v29 offset0:28 offset1:30
	s_waitcnt lgkmcnt(0)
	v_mov_b32_e32 v38, v3
	v_mov_b32_e32 v39, v16
	v_mov_b32_e32 v40, v17
	v_mov_b32_e32 v41, v18
	v_mov_b32_e32 v42, v19
	v_mov_b32_e32 v43, v20
	s_waitcnt vmcnt(0)
	v_mov_b32_e32 v0, v224
	v_mov_b32_e32 v28, v225
	v_mov_b32_e32 v24, v226
	v_mov_b32_e32 v26, v227
	v_mov_b32_e32 v30, v228
	s_cmpk_eq_i32 s40, 0x1000
	s_cbranch_scc1 .Lmy_dn_norp
	v_ashrrev_i32_e32 v220, 4, v46
	v_add_u32_e32 v222, v220, v47
	v_mov_b32_e32 v8, 0
	v_mov_b32_e32 v9, 0
	v_cmp_le_i32_e32 vcc, s33, v222
	v_cmp_gt_i32_e64 s[12:13], s72, v222
	v_mov_b32_e32 v10, 0
	v_mov_b32_e32 v11, 0
	v_mov_b64_e32 v[4:5], v[8:9]
	s_and_b64 s[14:15], vcc, s[12:13]
	v_and_b32_e32 v220, 15, v46
	v_mov_b64_e32 v[6:7], v[10:11]
	s_and_saveexec_b64 s[12:13], s[14:15]
	s_cbranch_execz .LBB0_675
	v_mad_i64_i32 v[222:223], s[14:15], v222, s51, 0
	s_add_u32 s14, s39, s40
	v_lshl_or_b32 v222, v220, 4, v222
	s_addc_u32 s15, s73, s41
	v_lshl_add_u64 v[222:223], s[14:15], 0, v[222:223]
	flat_load_dwordx4 v[4:7], v[222:223]

; __device__ __forceinline__ void phase_out(KP kp_){ asm volatile("" : "+s"(kp_)); const Params p=load_params(kp_);
;     ...
;     EPIG_BEGIN
;       float4 xa[8], ga[8];
;       EPIG_FOR int tok=rt*256+C0; xa[idx]=*(const float4*)(p.x+(size_t)tok*1024+ct*256+R0); ga[idx]=*(const float4*)(modv+(tok>>13)*3072+2048+ct*256+R0); EPIG_ENDFOR
;       EPIG_FOR f32x4 v=acc[ai][bj][m][n]; float4 xv=xa[idx], gt=ga[idx];
;         float4 r; r.x=xv.x+gt.x*v[0]; r.y=xv.y+gt.y*v[1]; r.z=xv.z+gt.z*v[2]; r.w=xv.w+gt.w*v[3];
;         *(float4*)(p.out+(size_t)(rt*256+C0)*1024+ct*256+R0)=r; EPIG_ENDFOR
.LBB0_1502:
	s_or_b64 exec, exec, s[24:25]
	v_and_b32_e32 v137, 15, v154
	v_bfe_u32 v138, v154, 6, 2
	v_lshl_add_u32 v137, v138, 5, v137
	v_add_u32_e32 v137, s22, v137
	v_bfe_u32 v138, v154, 4, 2
	v_lshrrev_b32_e32 v139, 8, v154
	v_lshl_add_u32 v138, v139, 4, v138
	v_lshlrev_b32_e32 v138, 2, v138
	v_add_u32_e32 v138, s35, v138
	v_lshlrev_b32_e32 v136, 2, v138
	v_lshl_add_u32 v140, v137, 12, v136
	v_mov_b32_e32 v141, v140
	v_add_u32_e32 v142, 0x10000, v140
	v_add_u32_e32 v143, 0x80000, v140
	v_add_u32_e32 v145, 0x90000, v140
	s_lshr_b32 s2, s75, 7
	s_mul_i32 s2, s2, 0x3000
	s_add_u32 s22, s42, s2
	s_addc_u32 s23, s43, 0
	s_add_u32 s22, s22, 0x3b82000
	s_addc_u32 s23, s23, 0
	s_add_i32 s75, s75, s76
	s_add_i32 s33, s33, s34
	v_readlane_b32 s2, v253, 40
	s_add_i32 s50, s50, s2
	global_load_dwordx4 v[156:159], v136, s[22:23] offset:0
	global_load_dwordx4 v[160:163], v136, s[22:23] offset:64
	global_load_dwordx4 v[164:167], v136, s[22:23] offset:128
	global_load_dwordx4 v[168:171], v136, s[22:23] offset:192
	global_load_dwordx4 v[172:175], v136, s[22:23] offset:512
	global_load_dwordx4 v[176:179], v136, s[22:23] offset:576
	global_load_dwordx4 v[180:183], v136, s[22:23] offset:640
	global_load_dwordx4 v[184:187], v136, s[22:23] offset:704
	global_load_dwordx4 v[188:191], v141, s[0:1] offset:0
	global_load_dwordx4 v[192:195], v142, s[0:1] offset:0
	global_load_dwordx4 v[196:199], v141, s[0:1] offset:64
	global_load_dwordx4 v[200:203], v142, s[0:1] offset:64
	global_load_dwordx4 v[204:207], v141, s[0:1] offset:128
	global_load_dwordx4 v[208:211], v142, s[0:1] offset:128
	global_load_dwordx4 v[212:215], v141, s[0:1] offset:192
	global_load_dwordx4 v[216:219], v142, s[0:1] offset:192
	global_load_dwordx4 v[220:223], v143, s[0:1] offset:0
	global_load_dwordx4 v[224:227], v145, s[0:1] offset:0
	global_load_dwordx4 v[228:231], v143, s[0:1] offset:64
	global_load_dwordx4 v[232:235], v145, s[0:1] offset:64
	global_load_dwordx4 v[236:239], v143, s[0:1] offset:128
	global_load_dwordx4 v[240:243], v145, s[0:1] offset:128
	global_load_dwordx4 v[244:247], v143, s[0:1] offset:192
	global_load_dwordx4 v[248:251], v145, s[0:1] offset:192
	s_waitcnt vmcnt(8)
	v_pk_fma_f32 v[96:97], v[96:97], v[156:157], v[188:189]
	v_pk_fma_f32 v[98:99], v[98:99], v[158:159], v[190:191]
	v_pk_fma_f32 v[100:101], v[100:101], v[156:157], v[192:193]
	v_pk_fma_f32 v[102:103], v[102:103], v[158:159], v[194:195]
	v_pk_fma_f32 v[104:105], v[104:105], v[160:161], v[196:197]
	v_pk_fma_f32 v[106:107], v[106:107], v[162:163], v[198:199]
	v_pk_fma_f32 v[108:109], v[108:109], v[160:161], v[200:201]
	v_pk_fma_f32 v[110:111], v[110:111], v[162:163], v[202:203]
	v_pk_fma_f32 v[112:113], v[112:113], v[164:165], v[204:205]
	v_pk_fma_f32 v[114:115], v[114:115], v[166:167], v[206:207]
	v_pk_fma_f32 v[116:117], v[116:117], v[164:165], v[208:209]
	v_pk_fma_f32 v[118:119], v[118:119], v[166:167], v[210:211]
	v_pk_fma_f32 v[120:121], v[120:121], v[168:169], v[212:213]
	v_pk_fma_f32 v[122:123], v[122:123], v[170:171], v[214:215]
	v_pk_fma_f32 v[124:125], v[124:125], v[168:169], v[216:217]
	v_pk_fma_f32 v[126:127], v[126:127], v[170:171], v[218:219]
	global_store_dwordx4 v141, v[96:99], s[40:41] offset:0
	global_store_dwordx4 v142, v[100:103], s[40:41] offset:0
	global_store_dwordx4 v141, v[104:107], s[40:41] offset:64
	global_store_dwordx4 v142, v[108:111], s[40:41] offset:64
	global_store_dwordx4 v141, v[112:115], s[40:41] offset:128
	global_store_dwordx4 v142, v[116:119], s[40:41] offset:128
	global_store_dwordx4 v141, v[120:123], s[40:41] offset:192
	global_store_dwordx4 v142, v[124:127], s[40:41] offset:192
	global_load_dwordx4 v[188:191], v141, s[0:1] offset:512
	global_load_dwordx4 v[192:195], v142, s[0:1] offset:512
	global_load_dwordx4 v[196:199], v141, s[0:1] offset:576
	global_load_dwordx4 v[200:203], v142, s[0:1] offset:576
	global_load_dwordx4 v[204:207], v141, s[0:1] offset:640
	global_load_dwordx4 v[208:211], v142, s[0:1] offset:640
	global_load_dwordx4 v[212:215], v141, s[0:1] offset:704
	global_load_dwordx4 v[216:219], v142, s[0:1] offset:704
	s_waitcnt vmcnt(16)
; __device__ __forceinline__ void phase_out(KP kp_){ asm volatile("" : "+s"(kp_)); const Params p=load_params(kp_);
;     ...
;       EPIG_FOR int tok=rt*256+C0; xa[idx]=*(const float4*)(p.x+(size_t)tok*1024+ct*256+R0); ga[idx]=*(const float4*)(modv+(tok>>13)*3072+2048+ct*256+R0); EPIG_ENDFOR
;       EPIG_FOR f32x4 v=acc[ai][bj][m][n]; float4 xv=xa[idx], gt=ga[idx];
;         float4 r; r.x=xv.x+gt.x*v[0]; r.y=xv.y+gt.y*v[1]; r.z=xv.z+gt.z*v[2]; r.w=xv.w+gt.w*v[3];
;         *(float4*)(p.out+(size_t)(rt*256+C0)*1024+ct*256+R0)=r; EPIG_ENDFOR
	v_pk_fma_f32 v[64:65], v[64:65], v[156:157], v[220:221]
	v_pk_fma_f32 v[66:67], v[66:67], v[158:159], v[222:223]
	v_pk_fma_f32 v[68:69], v[68:69], v[156:157], v[224:225]
	v_pk_fma_f32 v[70:71], v[70:71], v[158:159], v[226:227]
	v_pk_fma_f32 v[72:73], v[72:73], v[160:161], v[228:229]
	v_pk_fma_f32 v[74:75], v[74:75], v[162:163], v[230:231]
	v_pk_fma_f32 v[76:77], v[76:77], v[160:161], v[232:233]
	v_pk_fma_f32 v[78:79], v[78:79], v[162:163], v[234:235]
	v_pk_fma_f32 v[80:81], v[80:81], v[164:165], v[236:237]
	v_pk_fma_f32 v[82:83], v[82:83], v[166:167], v[238:239]
	v_pk_fma_f32 v[84:85], v[84:85], v[164:165], v[240:241]
	v_pk_fma_f32 v[86:87], v[86:87], v[166:167], v[242:243]
	v_pk_fma_f32 v[88:89], v[88:89], v[168:169], v[244:245]
	v_pk_fma_f32 v[90:91], v[90:91], v[170:171], v[246:247]
	v_pk_fma_f32 v[92:93], v[92:93], v[168:169], v[248:249]
	v_pk_fma_f32 v[94:95], v[94:95], v[170:171], v[250:251]
	global_store_dwordx4 v143, v[64:67], s[40:41] offset:0
	global_store_dwordx4 v145, v[68:71], s[40:41] offset:0
	global_store_dwordx4 v143, v[72:75], s[40:41] offset:64
	global_store_dwordx4 v145, v[76:79], s[40:41] offset:64
	global_store_dwordx4 v143, v[80:83], s[40:41] offset:128
	global_store_dwordx4 v145, v[84:87], s[40:41] offset:128
	global_store_dwordx4 v143, v[88:91], s[40:41] offset:192
	global_store_dwordx4 v145, v[92:95], s[40:41] offset:192
	global_load_dwordx4 v[220:223], v143, s[0:1] offset:512
	global_load_dwordx4 v[224:227], v145, s[0:1] offset:512
	global_load_dwordx4 v[228:231], v143, s[0:1] offset:576
	global_load_dwordx4 v[232:235], v145, s[0:1] offset:576
	global_load_dwordx4 v[236:239], v143, s[0:1] offset:640
	global_load_dwordx4 v[240:243], v145, s[0:1] offset:640
	global_load_dwordx4 v[244:247], v143, s[0:1] offset:704
	global_load_dwordx4 v[248:251], v145, s[0:1] offset:704
	s_waitcnt vmcnt(16)
	v_pk_fma_f32 v[32:33], v[32:33], v[172:173], v[188:189]
	v_pk_fma_f32 v[34:35], v[34:35], v[174:175], v[190:191]
	v_pk_fma_f32 v[36:37], v[36:37], v[172:173], v[192:193]
	v_pk_fma_f32 v[38:39], v[38:39], v[174:175], v[194:195]
	v_pk_fma_f32 v[40:41], v[40:41], v[176:177], v[196:197]
	v_pk_fma_f32 v[42:43], v[42:43], v[178:179], v[198:199]
	v_pk_fma_f32 v[44:45], v[44:45], v[176:177], v[200:201]
	v_pk_fma_f32 v[46:47], v[46:47], v[178:179], v[202:203]
	v_pk_fma_f32 v[48:49], v[48:49], v[180:181], v[204:205]
	v_pk_fma_f32 v[50:51], v[50:51], v[182:183], v[206:207]
	v_pk_fma_f32 v[52:53], v[52:53], v[180:181], v[208:209]
	v_pk_fma_f32 v[54:55], v[54:55], v[182:183], v[210:211]
	v_pk_fma_f32 v[56:57], v[56:57], v[184:185], v[212:213]
	v_pk_fma_f32 v[58:59], v[58:59], v[186:187], v[214:215]
	v_pk_fma_f32 v[60:61], v[60:61], v[184:185], v[216:217]
	v_pk_fma_f32 v[62:63], v[62:63], v[186:187], v[218:219]
	global_store_dwordx4 v141, v[32:35], s[40:41] offset:512
	global_store_dwordx4 v142, v[36:39], s[40:41] offset:512
	global_store_dwordx4 v141, v[40:43], s[40:41] offset:576
	global_store_dwordx4 v142, v[44:47], s[40:41] offset:576
	global_store_dwordx4 v141, v[48:51], s[40:41] offset:640
	global_store_dwordx4 v142, v[52:55], s[40:41] offset:640
	global_store_dwordx4 v141, v[56:59], s[40:41] offset:704
	global_store_dwordx4 v142, v[60:63], s[40:41] offset:704
	s_waitcnt vmcnt(8)
	v_pk_fma_f32 v[0:1], v[0:1], v[172:173], v[220:221]
	v_pk_fma_f32 v[2:3], v[2:3], v[174:175], v[222:223]
	v_pk_fma_f32 v[4:5], v[4:5], v[172:173], v[224:225]
	v_pk_fma_f32 v[6:7], v[6:7], v[174:175], v[226:227]
	v_pk_fma_f32 v[8:9], v[8:9], v[176:177], v[228:229]
	v_pk_fma_f32 v[10:11], v[10:11], v[178:179], v[230:231]
	v_pk_fma_f32 v[12:13], v[12:13], v[176:177], v[232:233]
	v_pk_fma_f32 v[14:15], v[14:15], v[178:179], v[234:235]
	v_pk_fma_f32 v[16:17], v[16:17], v[180:181], v[236:237]
	v_pk_fma_f32 v[18:19], v[18:19], v[182:183], v[238:239]
	v_pk_fma_f32 v[20:21], v[20:21], v[180:181], v[240:241]
	v_pk_fma_f32 v[22:23], v[22:23], v[182:183], v[242:243]
	v_pk_fma_f32 v[24:25], v[24:25], v[184:185], v[244:245]
	v_pk_fma_f32 v[26:27], v[26:27], v[186:187], v[246:247]
	v_pk_fma_f32 v[28:29], v[28:29], v[184:185], v[248:249]
	v_pk_fma_f32 v[30:31], v[30:31], v[186:187], v[250:251]
	global_store_dwordx4 v143, v[0:3], s[40:41] offset:512
	global_store_dwordx4 v145, v[4:7], s[40:41] offset:512
	global_store_dwordx4 v143, v[8:11], s[40:41] offset:576
	global_store_dwordx4 v145, v[12:15], s[40:41] offset:576
	global_store_dwordx4 v143, v[16:19], s[40:41] offset:640
	global_store_dwordx4 v145, v[20:23], s[40:41] offset:640
	global_store_dwordx4 v143, v[24:27], s[40:41] offset:704
	global_store_dwordx4 v145, v[28:31], s[40:41] offset:704
	s_cmpk_lt_i32 s75, 0x100
	s_cbranch_scc0 .LBB0_1509
